# phase 0 w_in tile loop on the same hand-written tile routine (static ids, loads two tiles ahead)
# speedup vs baseline: 1.0062x; 1.0006x over previous
.LBB0_8:
	s_or_b64 exec, exec, s[6:7]
	s_cmpk_gt_i32 s2, 0x47f
	s_cbranch_scc1 .LBB0_41
	s_waitcnt lgkmcnt(0)
	v_and_b32_e32 v1, 15, v0
	v_lshlrev_b32_e32 v2, 4, v1
	v_lshrrev_b32_e32 v3, 4, v0
	v_mul_u32_u24_e32 v4, 0x104, v3
	v_add_u32_e32 v20, v4, v2
	v_add_u32_e32 v21, 0x2080, v20
	v_add_u32_e32 v22, 0x2080, v21
	v_add_u32_e32 v23, 0x2080, v22
	v_add_u32_e32 v24, 0x2080, v23
	v_add_u32_e32 v25, 0x2080, v24
	v_add_u32_e32 v26, 0x2080, v25
	v_add_u32_e32 v27, 0x2080, v26
	v_and_b32_e32 v5, 7, v0
	v_lshlrev_b32_e32 v5, 3, v5
	v_lshrrev_b32_e32 v6, 3, v0
	v_mul_u32_u24_e32 v7, 0x104, v5
	v_lshl_add_u32 v7, v6, 2, v7
	v_lshlrev_b32_e32 v28, 2, v3
	v_lshlrev_b32_e32 v31, 1, v5
	v_lshlrev_b32_e32 v29, 12, v6
	v_add_u32_e32 v29, v29, v31
	s_mov_b32 s6, s2
	s_mul_i32 s7, s6, 0x1c72
	s_lshr_b32 s7, s7, 20
	s_mul_i32 s10, s7, 0x90
	s_sub_u32 s10, s6, s10
	s_mov_b32 s76, 0
	s_lshl_b32 s29, s10, 6
	s_cmp_lt_u32 s10, 55
	s_cbranch_scc1 .Lt0_ns_p0
	s_sub_u32 s29, s29, 64
	s_cmp_eq_u32 s10, 55
	s_cselect_b32 s76, 1, 0
.Lt0_ns_p0:
	s_mul_i32 s11, s7, 0x8f0000
	s_lshl_b32 s29, s29, 2
	s_add_u32 s11, s11, s29
	s_add_u32 s12, s40, s11
	s_addc_u32 s13, s41, 0
	s_mov_b32 s14, 0x8f00
	s_mov_b32 s15, 0x11e000
	s_lshl_b32 s11, s10, 18
	s_lshl_b32 s29, s7, 9
	s_add_u32 s11, s11, s29
	s_add_u32 s11, s11, 0x1600000
	s_add_u32 s16, s70, s11
	s_addc_u32 s17, s71, 0
	s_lshl_b32 s11, s7, 10
	s_add_u32 s20, s38, s11
	s_addc_u32 s21, s39, 0
	v_mul_u32_u24_e32 v180, s14, v3
	v_add_u32_e32 v180, v180, v2
	v_add_u32_e32 v181, s15, v180
	v_add_u32_e32 v182, s15, v181
	v_add_u32_e32 v183, s15, v182
	v_add_u32_e32 v184, s15, v183
	v_add_u32_e32 v185, s15, v184
	v_add_u32_e32 v186, s15, v185
	v_add_u32_e32 v187, s15, v186
	global_load_dword v72, v28, s[20:21]
	global_load_dword v73, v28, s[20:21] offset:128
	global_load_dword v74, v28, s[20:21] offset:256
	global_load_dword v75, v28, s[20:21] offset:384
	global_load_dword v76, v28, s[20:21] offset:512
	global_load_dword v77, v28, s[20:21] offset:640
	global_load_dword v78, v28, s[20:21] offset:768
	global_load_dword v79, v28, s[20:21] offset:896
	global_load_dwordx4 v[40:43], v180, s[12:13]
	global_load_dwordx4 v[44:47], v181, s[12:13]
	global_load_dwordx4 v[48:51], v182, s[12:13]
	global_load_dwordx4 v[52:55], v183, s[12:13]
	global_load_dwordx4 v[56:59], v184, s[12:13]
	global_load_dwordx4 v[60:63], v185, s[12:13]
	global_load_dwordx4 v[64:67], v186, s[12:13]
	global_load_dwordx4 v[68:71], v187, s[12:13]
	s_add_u32 s6, s2, 0x100
	s_mul_i32 s7, s6, 0x1c72
	s_lshr_b32 s7, s7, 20
	s_mul_i32 s10, s7, 0x90
	s_sub_u32 s10, s6, s10
	s_mov_b32 s77, 0
	s_lshl_b32 s29, s10, 6
	s_cmp_lt_u32 s10, 55
	s_cbranch_scc1 .Lt0_ns_p1
	s_sub_u32 s29, s29, 64
	s_cmp_eq_u32 s10, 55
	s_cselect_b32 s77, 1, 0
.Lt0_ns_p1:
	s_mul_i32 s11, s7, 0x8f0000
	s_lshl_b32 s29, s29, 2
	s_add_u32 s11, s11, s29
	s_add_u32 s12, s40, s11
	s_addc_u32 s13, s41, 0
	s_mov_b32 s14, 0x8f00
	s_mov_b32 s15, 0x11e000
	s_lshl_b32 s11, s10, 18
	s_lshl_b32 s29, s7, 9
	s_add_u32 s11, s11, s29
	s_add_u32 s11, s11, 0x1600000
	s_add_u32 s22, s70, s11
	s_addc_u32 s23, s71, 0
	s_lshl_b32 s11, s7, 10
	s_add_u32 s20, s38, s11
	s_addc_u32 s21, s39, 0
	v_mul_u32_u24_e32 v180, s14, v3
	v_add_u32_e32 v180, v180, v2
	v_add_u32_e32 v181, s15, v180
	v_add_u32_e32 v182, s15, v181
	v_add_u32_e32 v183, s15, v182
	v_add_u32_e32 v184, s15, v183
	v_add_u32_e32 v185, s15, v184
	v_add_u32_e32 v186, s15, v185
	v_add_u32_e32 v187, s15, v186
	global_load_dword v172, v28, s[20:21]
	global_load_dword v173, v28, s[20:21] offset:128
	global_load_dword v174, v28, s[20:21] offset:256
	global_load_dword v175, v28, s[20:21] offset:384
	global_load_dword v176, v28, s[20:21] offset:512
	global_load_dword v177, v28, s[20:21] offset:640
	global_load_dword v178, v28, s[20:21] offset:768
	global_load_dword v179, v28, s[20:21] offset:896
	global_load_dwordx4 v[140:143], v180, s[12:13]
	global_load_dwordx4 v[144:147], v181, s[12:13]
	global_load_dwordx4 v[148:151], v182, s[12:13]
	global_load_dwordx4 v[152:155], v183, s[12:13]
	global_load_dwordx4 v[156:159], v184, s[12:13]
	global_load_dwordx4 v[160:163], v185, s[12:13]
	global_load_dwordx4 v[164:167], v186, s[12:13]
	global_load_dwordx4 v[168:171], v187, s[12:13]
	s_add_u32 s81, s2, 0x200
	s_mov_b32 s79, 1
	s_waitcnt vmcnt(16)
.Lt0_st0:
	s_mov_b32 s80, 0
	s_cmp_ge_u32 s81, 0x480
	s_cbranch_scc1 .Lt0_pr0
	s_mov_b32 s6, s81
	s_mul_i32 s7, s6, 0x1c72
	s_lshr_b32 s7, s7, 20
	s_mul_i32 s10, s7, 0x90
	s_sub_u32 s10, s6, s10
	s_mov_b32 s78, 0
	s_lshl_b32 s29, s10, 6
	s_cmp_lt_u32 s10, 55
	s_cbranch_scc1 .Lt0_ns_n0
	s_sub_u32 s29, s29, 64
	s_cmp_eq_u32 s10, 55
	s_cselect_b32 s78, 1, 0
.Lt0_ns_n0:
	s_mul_i32 s11, s7, 0x8f0000
	s_lshl_b32 s29, s29, 2
	s_add_u32 s11, s11, s29
	s_add_u32 s12, s40, s11
	s_addc_u32 s13, s41, 0
	s_mov_b32 s14, 0x8f00
	s_mov_b32 s15, 0x11e000
	s_lshl_b32 s11, s10, 18
	s_lshl_b32 s29, s7, 9
	s_add_u32 s11, s11, s29
	s_add_u32 s11, s11, 0x1600000
	s_add_u32 s72, s70, s11
	s_addc_u32 s73, s71, 0
	s_lshl_b32 s11, s7, 10
	s_add_u32 s20, s38, s11
	s_addc_u32 s21, s39, 0
	v_mul_u32_u24_e32 v180, s14, v3
	v_add_u32_e32 v180, v180, v2
	v_add_u32_e32 v181, s15, v180
	v_add_u32_e32 v182, s15, v181
	v_add_u32_e32 v183, s15, v182
	v_add_u32_e32 v184, s15, v183
	v_add_u32_e32 v185, s15, v184
	v_add_u32_e32 v186, s15, v185
	v_add_u32_e32 v187, s15, v186
	global_load_dword v232, v28, s[20:21]
	global_load_dword v233, v28, s[20:21] offset:128
	global_load_dword v234, v28, s[20:21] offset:256
	global_load_dword v235, v28, s[20:21] offset:384
	global_load_dword v236, v28, s[20:21] offset:512
	global_load_dword v237, v28, s[20:21] offset:640
	global_load_dword v238, v28, s[20:21] offset:768
	global_load_dword v239, v28, s[20:21] offset:896
	global_load_dwordx4 v[200:203], v180, s[12:13]
	global_load_dwordx4 v[204:207], v181, s[12:13]
	global_load_dwordx4 v[208:211], v182, s[12:13]
	global_load_dwordx4 v[212:215], v183, s[12:13]
	global_load_dwordx4 v[216:219], v184, s[12:13]
	global_load_dwordx4 v[220:223], v185, s[12:13]
	global_load_dwordx4 v[224:227], v186, s[12:13]
	global_load_dwordx4 v[228:231], v187, s[12:13]
	s_add_u32 s81, s81, 0x100
	s_mov_b32 s80, 1
.Lt0_pr0:
	s_cmp_eq_u32 s76, 0
	s_cbranch_scc1 .Lt0_nz0
	v_mov_b32_e32 v40, 0
	v_mov_b32_e32 v41, 0
	v_mov_b32_e32 v42, 0
	v_mov_b32_e32 v43, 0
	v_mov_b32_e32 v44, 0
	v_mov_b32_e32 v45, 0
	v_mov_b32_e32 v46, 0
	v_mov_b32_e32 v47, 0
	v_mov_b32_e32 v48, 0
	v_mov_b32_e32 v49, 0
	v_mov_b32_e32 v50, 0
	v_mov_b32_e32 v51, 0
	v_mov_b32_e32 v52, 0
	v_mov_b32_e32 v53, 0
	v_mov_b32_e32 v54, 0
	v_mov_b32_e32 v55, 0
	v_mov_b32_e32 v56, 0
	v_mov_b32_e32 v57, 0
	v_mov_b32_e32 v58, 0
	v_mov_b32_e32 v59, 0
	v_mov_b32_e32 v60, 0
	v_mov_b32_e32 v61, 0
	v_mov_b32_e32 v62, 0
	v_mov_b32_e32 v63, 0
	v_mov_b32_e32 v64, 0
	v_mov_b32_e32 v65, 0
	v_mov_b32_e32 v66, 0
	v_mov_b32_e32 v67, 0
	v_mov_b32_e32 v68, 0
	v_mov_b32_e32 v69, 0
	v_mov_b32_e32 v70, 0
	v_mov_b32_e32 v71, 0
.Lt0_nz0:
	v_mul_f32_e32 v40, v40, v72
	v_mul_f32_e32 v41, v41, v72
	v_mul_f32_e32 v42, v42, v72
	v_mul_f32_e32 v43, v43, v72
	v_mul_f32_e32 v44, v44, v73
	v_mul_f32_e32 v45, v45, v73
	v_mul_f32_e32 v46, v46, v73
	v_mul_f32_e32 v47, v47, v73
	v_mul_f32_e32 v48, v48, v74
	v_mul_f32_e32 v49, v49, v74
	v_mul_f32_e32 v50, v50, v74
	v_mul_f32_e32 v51, v51, v74
	v_mul_f32_e32 v52, v52, v75
	v_mul_f32_e32 v53, v53, v75
	v_mul_f32_e32 v54, v54, v75
	v_mul_f32_e32 v55, v55, v75
	v_mul_f32_e32 v56, v56, v76
	v_mul_f32_e32 v57, v57, v76
	v_mul_f32_e32 v58, v58, v76
	v_mul_f32_e32 v59, v59, v76
	v_mul_f32_e32 v60, v60, v77
	v_mul_f32_e32 v61, v61, v77
	v_mul_f32_e32 v62, v62, v77
	v_mul_f32_e32 v63, v63, v77
	v_mul_f32_e32 v64, v64, v78
	v_mul_f32_e32 v65, v65, v78
	v_mul_f32_e32 v66, v66, v78
	v_mul_f32_e32 v67, v67, v78
	v_mul_f32_e32 v68, v68, v79
	v_mul_f32_e32 v69, v69, v79
	v_mul_f32_e32 v70, v70, v79
	v_mul_f32_e32 v71, v71, v79
	ds_write2_b32 v20, v40, v41 offset1:1
	ds_write2_b32 v20, v42, v43 offset0:2 offset1:3
	ds_write2_b32 v21, v44, v45 offset1:1
	ds_write2_b32 v21, v46, v47 offset0:2 offset1:3
	ds_write2_b32 v22, v48, v49 offset1:1
	ds_write2_b32 v22, v50, v51 offset0:2 offset1:3
	ds_write2_b32 v23, v52, v53 offset1:1
	ds_write2_b32 v23, v54, v55 offset0:2 offset1:3
	ds_write2_b32 v24, v56, v57 offset1:1
	ds_write2_b32 v24, v58, v59 offset0:2 offset1:3
	ds_write2_b32 v25, v60, v61 offset1:1
	ds_write2_b32 v25, v62, v63 offset0:2 offset1:3
	ds_write2_b32 v26, v64, v65 offset1:1
	ds_write2_b32 v26, v66, v67 offset0:2 offset1:3
	ds_write2_b32 v27, v68, v69 offset1:1
	ds_write2_b32 v27, v70, v71 offset0:2 offset1:3
	s_waitcnt lgkmcnt(0)
	s_barrier
	ds_read_b32 v8, v7 offset:0
	ds_read_b32 v9, v7 offset:260
	ds_read_b32 v10, v7 offset:520
	ds_read_b32 v11, v7 offset:780
	ds_read_b32 v12, v7 offset:1040
	ds_read_b32 v13, v7 offset:1300
	ds_read_b32 v14, v7 offset:1560
	ds_read_b32 v15, v7 offset:1820
	s_waitcnt lgkmcnt(0)
	v_cvt_pk_bf16_f32 v16, v8, v9
	v_cvt_pk_bf16_f32 v17, v10, v11
	v_cvt_pk_bf16_f32 v18, v12, v13
	v_cvt_pk_bf16_f32 v19, v14, v15
	global_store_dwordx4 v29, v[16:19], s[16:17]
	ds_read_b32 v8, v7 offset:16640
	ds_read_b32 v9, v7 offset:16900
	ds_read_b32 v10, v7 offset:17160
	ds_read_b32 v11, v7 offset:17420
	ds_read_b32 v12, v7 offset:17680
	ds_read_b32 v13, v7 offset:17940
	ds_read_b32 v14, v7 offset:18200
	ds_read_b32 v15, v7 offset:18460
	s_waitcnt lgkmcnt(0)
	v_cvt_pk_bf16_f32 v100, v8, v9
	v_cvt_pk_bf16_f32 v101, v10, v11
	v_cvt_pk_bf16_f32 v102, v12, v13
	v_cvt_pk_bf16_f32 v103, v14, v15
	global_store_dwordx4 v29, v[100:103], s[16:17] offset:128
	ds_read_b32 v8, v7 offset:33280
	ds_read_b32 v9, v7 offset:33540
	ds_read_b32 v10, v7 offset:33800
	ds_read_b32 v11, v7 offset:34060
	ds_read_b32 v12, v7 offset:34320
	ds_read_b32 v13, v7 offset:34580
	ds_read_b32 v14, v7 offset:34840
	ds_read_b32 v15, v7 offset:35100
	s_waitcnt lgkmcnt(0)
	v_cvt_pk_bf16_f32 v104, v8, v9
	v_cvt_pk_bf16_f32 v105, v10, v11
	v_cvt_pk_bf16_f32 v106, v12, v13
	v_cvt_pk_bf16_f32 v107, v14, v15
	global_store_dwordx4 v29, v[104:107], s[16:17] offset:256
	ds_read_b32 v8, v7 offset:49920
	ds_read_b32 v9, v7 offset:50180
	ds_read_b32 v10, v7 offset:50440
	ds_read_b32 v11, v7 offset:50700
	ds_read_b32 v12, v7 offset:50960
	ds_read_b32 v13, v7 offset:51220
	ds_read_b32 v14, v7 offset:51480
	ds_read_b32 v15, v7 offset:51740
	s_waitcnt lgkmcnt(0)
	v_cvt_pk_bf16_f32 v108, v8, v9
	v_cvt_pk_bf16_f32 v109, v10, v11
	v_cvt_pk_bf16_f32 v110, v12, v13
	v_cvt_pk_bf16_f32 v111, v14, v15
	global_store_dwordx4 v29, v[108:111], s[16:17] offset:384
	s_barrier
	s_cmp_eq_u32 s79, 0
	s_cbranch_scc1 .LBB0_41
	s_mov_b32 s79, s80
	s_cmp_eq_u32 s80, 0
	s_cbranch_scc1 .Lt0_w4_0
	s_waitcnt vmcnt(20)
	s_branch .Lt0_st1

.Lt0_st1:
	s_mov_b32 s80, 0
	s_cmp_ge_u32 s81, 0x480
	s_cbranch_scc1 .Lt0_pr1
	s_mov_b32 s6, s81
	s_mul_i32 s7, s6, 0x1c72
	s_lshr_b32 s7, s7, 20
	s_mul_i32 s10, s7, 0x90
	s_sub_u32 s10, s6, s10
	s_mov_b32 s76, 0
	s_lshl_b32 s29, s10, 6
	s_cmp_lt_u32 s10, 55
	s_cbranch_scc1 .Lt0_ns_n1
	s_sub_u32 s29, s29, 64
	s_cmp_eq_u32 s10, 55
	s_cselect_b32 s76, 1, 0
.Lt0_ns_n1:
	s_mul_i32 s11, s7, 0x8f0000
	s_lshl_b32 s29, s29, 2
	s_add_u32 s11, s11, s29
	s_add_u32 s12, s40, s11
	s_addc_u32 s13, s41, 0
	s_mov_b32 s14, 0x8f00
	s_mov_b32 s15, 0x11e000
	s_lshl_b32 s11, s10, 18
	s_lshl_b32 s29, s7, 9
	s_add_u32 s11, s11, s29
	s_add_u32 s11, s11, 0x1600000
	s_add_u32 s16, s70, s11
	s_addc_u32 s17, s71, 0
	s_lshl_b32 s11, s7, 10
	s_add_u32 s20, s38, s11
	s_addc_u32 s21, s39, 0
	v_mul_u32_u24_e32 v180, s14, v3
	v_add_u32_e32 v180, v180, v2
	v_add_u32_e32 v181, s15, v180
	v_add_u32_e32 v182, s15, v181
	v_add_u32_e32 v183, s15, v182
	v_add_u32_e32 v184, s15, v183
	v_add_u32_e32 v185, s15, v184
	v_add_u32_e32 v186, s15, v185
	v_add_u32_e32 v187, s15, v186
	global_load_dword v72, v28, s[20:21]
	global_load_dword v73, v28, s[20:21] offset:128
	global_load_dword v74, v28, s[20:21] offset:256
	global_load_dword v75, v28, s[20:21] offset:384
	global_load_dword v76, v28, s[20:21] offset:512
	global_load_dword v77, v28, s[20:21] offset:640
	global_load_dword v78, v28, s[20:21] offset:768
	global_load_dword v79, v28, s[20:21] offset:896
	global_load_dwordx4 v[40:43], v180, s[12:13]
	global_load_dwordx4 v[44:47], v181, s[12:13]
	global_load_dwordx4 v[48:51], v182, s[12:13]
	global_load_dwordx4 v[52:55], v183, s[12:13]
	global_load_dwordx4 v[56:59], v184, s[12:13]
	global_load_dwordx4 v[60:63], v185, s[12:13]
	global_load_dwordx4 v[64:67], v186, s[12:13]
	global_load_dwordx4 v[68:71], v187, s[12:13]
	s_add_u32 s81, s81, 0x100
	s_mov_b32 s80, 1
.Lt0_pr1:
	s_cmp_eq_u32 s77, 0
	s_cbranch_scc1 .Lt0_nz1
	v_mov_b32_e32 v140, 0
	v_mov_b32_e32 v141, 0
	v_mov_b32_e32 v142, 0
	v_mov_b32_e32 v143, 0
	v_mov_b32_e32 v144, 0
	v_mov_b32_e32 v145, 0
	v_mov_b32_e32 v146, 0
	v_mov_b32_e32 v147, 0
	v_mov_b32_e32 v148, 0
	v_mov_b32_e32 v149, 0
	v_mov_b32_e32 v150, 0
	v_mov_b32_e32 v151, 0
	v_mov_b32_e32 v152, 0
	v_mov_b32_e32 v153, 0
	v_mov_b32_e32 v154, 0
	v_mov_b32_e32 v155, 0
	v_mov_b32_e32 v156, 0
	v_mov_b32_e32 v157, 0
	v_mov_b32_e32 v158, 0
	v_mov_b32_e32 v159, 0
	v_mov_b32_e32 v160, 0
	v_mov_b32_e32 v161, 0
	v_mov_b32_e32 v162, 0
	v_mov_b32_e32 v163, 0
	v_mov_b32_e32 v164, 0
	v_mov_b32_e32 v165, 0
	v_mov_b32_e32 v166, 0
	v_mov_b32_e32 v167, 0
	v_mov_b32_e32 v168, 0
	v_mov_b32_e32 v169, 0
	v_mov_b32_e32 v170, 0
	v_mov_b32_e32 v171, 0
.Lt0_nz1:
	v_mul_f32_e32 v140, v140, v172
	v_mul_f32_e32 v141, v141, v172
	v_mul_f32_e32 v142, v142, v172
	v_mul_f32_e32 v143, v143, v172
	v_mul_f32_e32 v144, v144, v173
	v_mul_f32_e32 v145, v145, v173
	v_mul_f32_e32 v146, v146, v173
	v_mul_f32_e32 v147, v147, v173
	v_mul_f32_e32 v148, v148, v174
	v_mul_f32_e32 v149, v149, v174
	v_mul_f32_e32 v150, v150, v174
	v_mul_f32_e32 v151, v151, v174
	v_mul_f32_e32 v152, v152, v175
	v_mul_f32_e32 v153, v153, v175
	v_mul_f32_e32 v154, v154, v175
	v_mul_f32_e32 v155, v155, v175
	v_mul_f32_e32 v156, v156, v176
	v_mul_f32_e32 v157, v157, v176
	v_mul_f32_e32 v158, v158, v176
	v_mul_f32_e32 v159, v159, v176
	v_mul_f32_e32 v160, v160, v177
	v_mul_f32_e32 v161, v161, v177
	v_mul_f32_e32 v162, v162, v177
	v_mul_f32_e32 v163, v163, v177
	v_mul_f32_e32 v164, v164, v178
	v_mul_f32_e32 v165, v165, v178
	v_mul_f32_e32 v166, v166, v178
	v_mul_f32_e32 v167, v167, v178
	v_mul_f32_e32 v168, v168, v179
	v_mul_f32_e32 v169, v169, v179
	v_mul_f32_e32 v170, v170, v179
	v_mul_f32_e32 v171, v171, v179
	ds_write2_b32 v20, v140, v141 offset1:1
	ds_write2_b32 v20, v142, v143 offset0:2 offset1:3
	ds_write2_b32 v21, v144, v145 offset1:1
	ds_write2_b32 v21, v146, v147 offset0:2 offset1:3
	ds_write2_b32 v22, v148, v149 offset1:1
	ds_write2_b32 v22, v150, v151 offset0:2 offset1:3
	ds_write2_b32 v23, v152, v153 offset1:1
	ds_write2_b32 v23, v154, v155 offset0:2 offset1:3
	ds_write2_b32 v24, v156, v157 offset1:1
	ds_write2_b32 v24, v158, v159 offset0:2 offset1:3
	ds_write2_b32 v25, v160, v161 offset1:1
	ds_write2_b32 v25, v162, v163 offset0:2 offset1:3
	ds_write2_b32 v26, v164, v165 offset1:1
	ds_write2_b32 v26, v166, v167 offset0:2 offset1:3
	ds_write2_b32 v27, v168, v169 offset1:1
	ds_write2_b32 v27, v170, v171 offset0:2 offset1:3
	s_waitcnt lgkmcnt(0)
	s_barrier
	ds_read_b32 v8, v7 offset:0
	ds_read_b32 v9, v7 offset:260
	ds_read_b32 v10, v7 offset:520
	ds_read_b32 v11, v7 offset:780
	ds_read_b32 v12, v7 offset:1040
	ds_read_b32 v13, v7 offset:1300
	ds_read_b32 v14, v7 offset:1560
	ds_read_b32 v15, v7 offset:1820
	s_waitcnt lgkmcnt(0)
	v_cvt_pk_bf16_f32 v16, v8, v9
	v_cvt_pk_bf16_f32 v17, v10, v11
	v_cvt_pk_bf16_f32 v18, v12, v13
	v_cvt_pk_bf16_f32 v19, v14, v15
	global_store_dwordx4 v29, v[16:19], s[22:23]
	ds_read_b32 v8, v7 offset:16640
	ds_read_b32 v9, v7 offset:16900
	ds_read_b32 v10, v7 offset:17160
	ds_read_b32 v11, v7 offset:17420
	ds_read_b32 v12, v7 offset:17680
	ds_read_b32 v13, v7 offset:17940
	ds_read_b32 v14, v7 offset:18200
	ds_read_b32 v15, v7 offset:18460
	s_waitcnt lgkmcnt(0)
	v_cvt_pk_bf16_f32 v100, v8, v9
	v_cvt_pk_bf16_f32 v101, v10, v11
	v_cvt_pk_bf16_f32 v102, v12, v13
	v_cvt_pk_bf16_f32 v103, v14, v15
	global_store_dwordx4 v29, v[100:103], s[22:23] offset:128
	ds_read_b32 v8, v7 offset:33280
	ds_read_b32 v9, v7 offset:33540
	ds_read_b32 v10, v7 offset:33800
	ds_read_b32 v11, v7 offset:34060
	ds_read_b32 v12, v7 offset:34320
	ds_read_b32 v13, v7 offset:34580
	ds_read_b32 v14, v7 offset:34840
	ds_read_b32 v15, v7 offset:35100
	s_waitcnt lgkmcnt(0)
	v_cvt_pk_bf16_f32 v104, v8, v9
	v_cvt_pk_bf16_f32 v105, v10, v11
	v_cvt_pk_bf16_f32 v106, v12, v13
	v_cvt_pk_bf16_f32 v107, v14, v15
	global_store_dwordx4 v29, v[104:107], s[22:23] offset:256
	ds_read_b32 v8, v7 offset:49920
	ds_read_b32 v9, v7 offset:50180
	ds_read_b32 v10, v7 offset:50440
	ds_read_b32 v11, v7 offset:50700
	ds_read_b32 v12, v7 offset:50960
	ds_read_b32 v13, v7 offset:51220
	ds_read_b32 v14, v7 offset:51480
	ds_read_b32 v15, v7 offset:51740
	s_waitcnt lgkmcnt(0)
	v_cvt_pk_bf16_f32 v108, v8, v9
	v_cvt_pk_bf16_f32 v109, v10, v11
	v_cvt_pk_bf16_f32 v110, v12, v13
	v_cvt_pk_bf16_f32 v111, v14, v15
	global_store_dwordx4 v29, v[108:111], s[22:23] offset:384
	s_barrier
	s_cmp_eq_u32 s79, 0
	s_cbranch_scc1 .LBB0_41
	s_mov_b32 s79, s80
	s_cmp_eq_u32 s80, 0
	s_cbranch_scc1 .Lt0_w4_1
	s_waitcnt vmcnt(20)
	s_branch .Lt0_st2

.Lt0_st2:
	s_mov_b32 s80, 0
	s_cmp_ge_u32 s81, 0x480
	s_cbranch_scc1 .Lt0_pr2
	s_mov_b32 s6, s81
	s_mul_i32 s7, s6, 0x1c72
	s_lshr_b32 s7, s7, 20
	s_mul_i32 s10, s7, 0x90
	s_sub_u32 s10, s6, s10
	s_mov_b32 s77, 0
	s_lshl_b32 s29, s10, 6
	s_cmp_lt_u32 s10, 55
	s_cbranch_scc1 .Lt0_ns_n2
	s_sub_u32 s29, s29, 64
	s_cmp_eq_u32 s10, 55
	s_cselect_b32 s77, 1, 0
.Lt0_ns_n2:
	s_mul_i32 s11, s7, 0x8f0000
	s_lshl_b32 s29, s29, 2
	s_add_u32 s11, s11, s29
	s_add_u32 s12, s40, s11
	s_addc_u32 s13, s41, 0
	s_mov_b32 s14, 0x8f00
	s_mov_b32 s15, 0x11e000
	s_lshl_b32 s11, s10, 18
	s_lshl_b32 s29, s7, 9
	s_add_u32 s11, s11, s29
	s_add_u32 s11, s11, 0x1600000
	s_add_u32 s22, s70, s11
	s_addc_u32 s23, s71, 0
	s_lshl_b32 s11, s7, 10
	s_add_u32 s20, s38, s11
	s_addc_u32 s21, s39, 0
	v_mul_u32_u24_e32 v180, s14, v3
	v_add_u32_e32 v180, v180, v2
	v_add_u32_e32 v181, s15, v180
	v_add_u32_e32 v182, s15, v181
	v_add_u32_e32 v183, s15, v182
	v_add_u32_e32 v184, s15, v183
	v_add_u32_e32 v185, s15, v184
	v_add_u32_e32 v186, s15, v185
	v_add_u32_e32 v187, s15, v186
	global_load_dword v172, v28, s[20:21]
	global_load_dword v173, v28, s[20:21] offset:128
	global_load_dword v174, v28, s[20:21] offset:256
	global_load_dword v175, v28, s[20:21] offset:384
	global_load_dword v176, v28, s[20:21] offset:512
	global_load_dword v177, v28, s[20:21] offset:640
	global_load_dword v178, v28, s[20:21] offset:768
	global_load_dword v179, v28, s[20:21] offset:896
	global_load_dwordx4 v[140:143], v180, s[12:13]
	global_load_dwordx4 v[144:147], v181, s[12:13]
	global_load_dwordx4 v[148:151], v182, s[12:13]
	global_load_dwordx4 v[152:155], v183, s[12:13]
	global_load_dwordx4 v[156:159], v184, s[12:13]
	global_load_dwordx4 v[160:163], v185, s[12:13]
	global_load_dwordx4 v[164:167], v186, s[12:13]
	global_load_dwordx4 v[168:171], v187, s[12:13]
	s_add_u32 s81, s81, 0x100
	s_mov_b32 s80, 1
.Lt0_pr2:
	s_cmp_eq_u32 s78, 0
	s_cbranch_scc1 .Lt0_nz2
	v_mov_b32_e32 v200, 0
	v_mov_b32_e32 v201, 0
	v_mov_b32_e32 v202, 0
	v_mov_b32_e32 v203, 0
	v_mov_b32_e32 v204, 0
	v_mov_b32_e32 v205, 0
	v_mov_b32_e32 v206, 0
	v_mov_b32_e32 v207, 0
	v_mov_b32_e32 v208, 0
	v_mov_b32_e32 v209, 0
	v_mov_b32_e32 v210, 0
	v_mov_b32_e32 v211, 0
	v_mov_b32_e32 v212, 0
	v_mov_b32_e32 v213, 0
	v_mov_b32_e32 v214, 0
	v_mov_b32_e32 v215, 0
	v_mov_b32_e32 v216, 0
	v_mov_b32_e32 v217, 0
	v_mov_b32_e32 v218, 0
	v_mov_b32_e32 v219, 0
	v_mov_b32_e32 v220, 0
	v_mov_b32_e32 v221, 0
	v_mov_b32_e32 v222, 0
	v_mov_b32_e32 v223, 0
	v_mov_b32_e32 v224, 0
	v_mov_b32_e32 v225, 0
	v_mov_b32_e32 v226, 0
	v_mov_b32_e32 v227, 0
	v_mov_b32_e32 v228, 0
	v_mov_b32_e32 v229, 0
	v_mov_b32_e32 v230, 0
	v_mov_b32_e32 v231, 0
.Lt0_nz2:
	v_mul_f32_e32 v200, v200, v232
	v_mul_f32_e32 v201, v201, v232
	v_mul_f32_e32 v202, v202, v232
	v_mul_f32_e32 v203, v203, v232
	v_mul_f32_e32 v204, v204, v233
	v_mul_f32_e32 v205, v205, v233
	v_mul_f32_e32 v206, v206, v233
	v_mul_f32_e32 v207, v207, v233
	v_mul_f32_e32 v208, v208, v234
	v_mul_f32_e32 v209, v209, v234
	v_mul_f32_e32 v210, v210, v234
	v_mul_f32_e32 v211, v211, v234
	v_mul_f32_e32 v212, v212, v235
	v_mul_f32_e32 v213, v213, v235
	v_mul_f32_e32 v214, v214, v235
	v_mul_f32_e32 v215, v215, v235
	v_mul_f32_e32 v216, v216, v236
	v_mul_f32_e32 v217, v217, v236
	v_mul_f32_e32 v218, v218, v236
	v_mul_f32_e32 v219, v219, v236
	v_mul_f32_e32 v220, v220, v237
	v_mul_f32_e32 v221, v221, v237
	v_mul_f32_e32 v222, v222, v237
	v_mul_f32_e32 v223, v223, v237
	v_mul_f32_e32 v224, v224, v238
	v_mul_f32_e32 v225, v225, v238
	v_mul_f32_e32 v226, v226, v238
	v_mul_f32_e32 v227, v227, v238
	v_mul_f32_e32 v228, v228, v239
	v_mul_f32_e32 v229, v229, v239
	v_mul_f32_e32 v230, v230, v239
	v_mul_f32_e32 v231, v231, v239
	ds_write2_b32 v20, v200, v201 offset1:1
	ds_write2_b32 v20, v202, v203 offset0:2 offset1:3
	ds_write2_b32 v21, v204, v205 offset1:1
	ds_write2_b32 v21, v206, v207 offset0:2 offset1:3
	ds_write2_b32 v22, v208, v209 offset1:1
	ds_write2_b32 v22, v210, v211 offset0:2 offset1:3
	ds_write2_b32 v23, v212, v213 offset1:1
	ds_write2_b32 v23, v214, v215 offset0:2 offset1:3
	ds_write2_b32 v24, v216, v217 offset1:1
	ds_write2_b32 v24, v218, v219 offset0:2 offset1:3
	ds_write2_b32 v25, v220, v221 offset1:1
	ds_write2_b32 v25, v222, v223 offset0:2 offset1:3
	ds_write2_b32 v26, v224, v225 offset1:1
	ds_write2_b32 v26, v226, v227 offset0:2 offset1:3
	ds_write2_b32 v27, v228, v229 offset1:1
	ds_write2_b32 v27, v230, v231 offset0:2 offset1:3
	s_waitcnt lgkmcnt(0)
	s_barrier
	ds_read_b32 v8, v7 offset:0
	ds_read_b32 v9, v7 offset:260
	ds_read_b32 v10, v7 offset:520
	ds_read_b32 v11, v7 offset:780
	ds_read_b32 v12, v7 offset:1040
	ds_read_b32 v13, v7 offset:1300
	ds_read_b32 v14, v7 offset:1560
	ds_read_b32 v15, v7 offset:1820
	s_waitcnt lgkmcnt(0)
	v_cvt_pk_bf16_f32 v16, v8, v9
	v_cvt_pk_bf16_f32 v17, v10, v11
	v_cvt_pk_bf16_f32 v18, v12, v13
	v_cvt_pk_bf16_f32 v19, v14, v15
	global_store_dwordx4 v29, v[16:19], s[72:73]
	ds_read_b32 v8, v7 offset:16640
	ds_read_b32 v9, v7 offset:16900
	ds_read_b32 v10, v7 offset:17160
	ds_read_b32 v11, v7 offset:17420
	ds_read_b32 v12, v7 offset:17680
	ds_read_b32 v13, v7 offset:17940
	ds_read_b32 v14, v7 offset:18200
	ds_read_b32 v15, v7 offset:18460
	s_waitcnt lgkmcnt(0)
	v_cvt_pk_bf16_f32 v100, v8, v9
	v_cvt_pk_bf16_f32 v101, v10, v11
	v_cvt_pk_bf16_f32 v102, v12, v13
	v_cvt_pk_bf16_f32 v103, v14, v15
	global_store_dwordx4 v29, v[100:103], s[72:73] offset:128
	ds_read_b32 v8, v7 offset:33280
	ds_read_b32 v9, v7 offset:33540
	ds_read_b32 v10, v7 offset:33800
	ds_read_b32 v11, v7 offset:34060
	ds_read_b32 v12, v7 offset:34320
	ds_read_b32 v13, v7 offset:34580
	ds_read_b32 v14, v7 offset:34840
	ds_read_b32 v15, v7 offset:35100
	s_waitcnt lgkmcnt(0)
	v_cvt_pk_bf16_f32 v104, v8, v9
	v_cvt_pk_bf16_f32 v105, v10, v11
	v_cvt_pk_bf16_f32 v106, v12, v13
	v_cvt_pk_bf16_f32 v107, v14, v15
	global_store_dwordx4 v29, v[104:107], s[72:73] offset:256
	ds_read_b32 v8, v7 offset:49920
	ds_read_b32 v9, v7 offset:50180
	ds_read_b32 v10, v7 offset:50440
	ds_read_b32 v11, v7 offset:50700
	ds_read_b32 v12, v7 offset:50960
	ds_read_b32 v13, v7 offset:51220
	ds_read_b32 v14, v7 offset:51480
	ds_read_b32 v15, v7 offset:51740
	s_waitcnt lgkmcnt(0)
	v_cvt_pk_bf16_f32 v108, v8, v9
	v_cvt_pk_bf16_f32 v109, v10, v11
	v_cvt_pk_bf16_f32 v110, v12, v13
	v_cvt_pk_bf16_f32 v111, v14, v15
	global_store_dwordx4 v29, v[108:111], s[72:73] offset:384
	s_barrier
	s_cmp_eq_u32 s79, 0
	s_cbranch_scc1 .LBB0_41
	s_mov_b32 s79, s80
	s_cmp_eq_u32 s80, 0
	s_cbranch_scc1 .Lt0_w4_2
	s_waitcnt vmcnt(20)
	s_branch .Lt0_st0
.Lt0_w4_2:
	s_waitcnt vmcnt(4)
	s_branch .Lt0_st0
.LBB0_41:
	v_lshl_or_b32 v1, s2, 9, v0
	s_mov_b32 s6, 0x70000
	v_cmp_gt_i32_e32 vcc, s6, v1
	s_and_saveexec_b64 s[6:7], vcc
	s_cbranch_execz .LBB0_52
	s_add_u32 s10, s70, 0x7600000
	s_addc_u32 s11, s71, 0
	s_add_u32 s12, s70, 0x7630000
	s_addc_u32 s13, s71, 0
	s_add_u32 s14, s70, 0x7660000
	s_addc_u32 s15, s71, 0
	s_waitcnt lgkmcnt(0)
	s_lshl_b32 s22, s3, 9
	s_mov_b64 s[16:17], 0
	s_movk_i32 s23, 0x5f
	v_mov_b32_e32 v3, 0
	s_movk_i32 s24, 0xbf
	s_movk_i32 s25, 0x60
	s_mov_b32 s26, 0x6ffff
	s_branch .LBB0_44

.Lat_pv_done:
	s_nop 7
	v_cvt_pk_bf16_f32 v22, v240, v240
	v_cvt_pk_bf16_f32 v23, v241, v241
	v_cvt_pk_bf16_f32 v24, v242, v242
	v_cvt_pk_bf16_f32 v25, v243, v243
	v_cvt_pk_bf16_f32 v26, v244, v244
	v_cvt_pk_bf16_f32 v27, v245, v245
	v_cvt_pk_bf16_f32 v28, v246, v246
	v_cvt_pk_bf16_f32 v29, v247, v247
	v_cvt_pk_bf16_f32 v134, v248, v248
	v_cvt_pk_bf16_f32 v135, v249, v249
	v_cvt_pk_bf16_f32 v136, v250, v250
	v_cvt_pk_bf16_f32 v137, v251, v251
	v_cvt_pk_bf16_f32 v138, v120, v120
	v_cvt_pk_bf16_f32 v139, v121, v121
	v_cvt_pk_bf16_f32 v150, v122, v122
	v_cvt_pk_bf16_f32 v151, v123, v123
	global_store_short v17, v22, s[20:21]
	global_store_short v17, v23, s[20:21] offset:2048
	global_store_short v18, v24, s[20:21]
	global_store_short v18, v25, s[20:21] offset:2048
	global_store_short v17, v26, s[20:21] offset:32
	global_store_short v17, v27, s[20:21] offset:2080
	global_store_short v18, v28, s[20:21] offset:32
	global_store_short v18, v29, s[20:21] offset:2080
	global_store_short v17, v134, s[20:21] offset:64
	global_store_short v17, v135, s[20:21] offset:2112
	global_store_short v18, v136, s[20:21] offset:64
	global_store_short v18, v137, s[20:21] offset:2112
	global_store_short v17, v138, s[20:21] offset:96
	global_store_short v17, v139, s[20:21] offset:2144
	global_store_short v18, v150, s[20:21] offset:96
	global_store_short v18, v151, s[20:21] offset:2144
	s_add_u32 s3, s3, s6
	s_cmp_lt_u32 s3, 0x2000
	s_cbranch_scc1 .Lat_loop
	v_and_b32_e32 v10, 15, v0
	s_add_u32 s74, s0, 0xd8
	s_addc_u32 s75, s1, 0
	v_mov_b64_e32 v[2:3], s[74:75]
	s_mov_b64 s[64:65], exec
	s_nop 0
.LBB0_388:
	s_or_b64 exec, exec, s[64:65]
	s_sub_i32 s6, s2, 32
	v_readfirstlane_b32 s7, v0
	s_cmpk_gt_u32 s6, 0x17f
	v_lshlrev_b32_e32 v157, 2, v0
	s_waitcnt lgkmcnt(0)
	s_barrier
	s_cbranch_scc1 .LBB0_405
	v_lshrrev_b32_e32 v1, 5, v0
	global_load_dword v15, v[2:3], off
	v_and_b32_e32 v2, 4, v1
	v_lshrrev_b32_e32 v1, 1, v0
	v_bfe_u32 v3, v0, 2, 2
	v_and_b32_e32 v1, 24, v1
	s_add_u32 s8, s70, 0x10900000
	v_or3_b32 v2, v2, v3, v1
	v_lshlrev_b32_e32 v3, 4, v0
	s_addc_u32 s9, s71, 0
	v_or_b32_e32 v11, 0x2000, v3
	s_add_u32 s10, s70, 0x2e00000
	v_lshrrev_b32_e32 v4, 7, v11
	s_movk_i32 s3, 0x60
	s_waitcnt vmcnt(18)
	v_bfe_u32 v14, v0, 2, 4
	s_movk_i32 s12, 0x70
	s_addc_u32 s11, s71, 0
	v_and_or_b32 v5, v4, s3, v2
	v_and_or_b32 v4, v4, s12, v14
	s_and_b32 s12, s2, 7
	s_lshr_b32 s13, s6, 3
	s_mul_i32 s12, s12, 48
	s_add_i32 s12, s12, s13
	s_mul_i32 s13, s12, 0xaaab
	s_lshr_b32 s13, s13, 22
	s_lshl_b32 s14, s13, 3
	s_mulk_i32 s13, 0x60
	s_sub_i32 s12, s12, s13
	s_and_b32 s13, s12, 7
	v_and_b32_e32 v6, 32, v0
	s_or_b32 s18, s14, s13
	s_lshr_b32 s22, s7, 6
	v_bitop3_b32 v12, v3, v6, 48 bitop3:0x6c
	v_and_b32_e32 v13, 64, v0
	s_bfe_u32 s19, s12, 0x50003
	s_and_b32 s12, s18, 0x1fff
	s_mov_b32 s13, 0
	s_lshr_b32 s24, s7, 8
	s_lshl_b32 s42, s22, 10
	v_or_b32_e32 v3, v12, v13
	s_lshl_b64 s[14:15], s[12:13], 20
	s_lshl_b32 s12, s19, 20
	v_lshl_or_b32 v134, v4, 12, v3
	v_lshrrev_b32_e32 v4, 3, v0
	s_add_u32 s30, s10, s12
	v_and_or_b32 v2, v4, 32, v2
	s_addc_u32 s31, s11, 0
	s_add_i32 s12, s42, 0
	v_lshl_or_b32 v136, v2, 12, v3
	s_add_i32 m0, s12, 0x10000
	v_lshl_or_b32 v132, v5, 12, v3
	global_load_lds_dwordx4 v136, s[30:31]
	s_add_i32 m0, s12, 0x12000
	s_add_u32 s16, s30, 0x80000
	global_load_lds_dwordx4 v132, s[30:31]
	s_addc_u32 s17, s31, 0
	s_add_i32 m0, s12, 0x14000
	v_and_or_b32 v2, v4, 48, v14
	global_load_lds_dwordx4 v136, s[16:17]
	s_add_i32 m0, s12, 0x16000
	s_add_u32 s44, s8, s14
	s_addc_u32 s45, s9, s15
	s_add_i32 s78, s12, 0x2000
	v_lshl_or_b32 v138, v2, 12, v3
	global_load_lds_dwordx4 v132, s[16:17]
	s_mov_b32 m0, s12
	s_add_u32 s14, s44, 0x80000
	global_load_lds_dwordx4 v138, s[44:45]
	s_mov_b32 m0, s78
	s_addc_u32 s15, s45, 0
	s_add_i32 s79, s12, 0x4000
	global_load_lds_dwordx4 v134, s[44:45]
	s_mov_b32 m0, s79
	s_add_i32 s80, s12, 0x6000
	global_load_lds_dwordx4 v138, s[14:15]
	s_mov_b32 m0, s80
	v_mov_b32_e32 v137, 0
	global_load_lds_dwordx4 v134, s[14:15]
	v_mov_b32_e32 v133, v137
	v_mov_b32_e32 v139, v137
	v_mov_b32_e32 v135, v137
	s_cmp_eq_u32 s24, 1
	v_lshl_add_u64 v[8:9], s[30:31], 0, v[136:137]
	v_lshl_add_u64 v[4:5], s[30:31], 0, v[132:133]
	s_mov_b64 s[14:15], 0x80000
	v_lshl_add_u64 v[2:3], s[44:45], 0, v[138:139]
	s_cselect_b64 s[16:17], -1, 0
	s_cmp_lg_u32 s24, 1
	v_lshl_add_u64 v[6:7], s[44:45], 0, v[134:135]
	s_cbranch_scc1 .LBB0_391
	s_barrier
